# v89 + attention loops: rescale decision from per-lane partial row max (wave-uniform any() is identical); ds_bpermute + wait + max moved into the rare rescale block
# baseline (speedup 1.0000x reference)
; #define LAS __attribute__((address_space(3)))
; DI float shfl_xor_l(float v, int lane, int m) { return __int_as_float(__builtin_amdgcn_ds_bpermute((lane ^ m) << 2, __float_as_int(v))); }
; #define A_LOAD(kt) do { const size_t ko = (size_t)(kt) * 64; st0 = *(const u32x4*)(kn_src + ko * 2048); st1 = *(const u32x4*)(kn_src + (ko + 32) * 2048); \
;         st2 = *(const u32x4*)(kr_src + ko * 64); st3 = *(const u32x4*)(v_src + ko); st4 = *(const u32x4*)(v_src + ko + (size_t)64 * 8192); } while (0)
; #define VLD(dst, j, dt) do { LAS unsigned char* va_ = vb + (32 * (dt) + n) * VROW + (16 * (j) + 4 * g) * 2; const u32x2 lo_ = *(const LAS u32x2*)(va_), hi_ = *(const LAS u32x2*)(va_ + 16); dst = (u32x4){lo_.x, lo_.y, hi_.x, hi_.y}; } while (0)
; DI void attn_unit(LAS unsigned char* lds, int wid, int b, int h, int qb) {
;     ...
;         if (kt + 1 < nkt) A_LOAD(kt + 1);
;         if (kt <= cq) {
;             LAS unsigned char* kb = lds + buf * ABUF; LAS unsigned char* vb = kb + KBYTES;
;             f32x16 s0, s1;
; #pragma unroll
;             for (int i = 0; i < 16; ++i) { s0[i] = 0.f; s1[i] = 0.f; }
;     ...
;             bf16x8 ka[3][2];
;             ka[0][0] = KLD(0, 0); ka[0][1] = KLD(0, 1); ka[1][0] = KLD(1, 0); ka[1][1] = KLD(1, 1);
; #pragma unroll
;             for (int ks = 0; ks < 12; ++ks) {
;                 if (ks + 2 < 12) { ka[(ks + 2) % 3][0] = KLD(ks + 2, 0); ka[(ks + 2) % 3][1] = KLD(ks + 2, 1); }
;                 s0 = __builtin_amdgcn_mfma_f32_32x32x16_bf16(ka[ks % 3][0], qf[ks], s0, 0, 0, 0); s1 = __builtin_amdgcn_mfma_f32_32x32x16_bf16(ka[ks % 3][1], qf[ks], s1, 0, 0, 0);
;                 __builtin_amdgcn_sched_barrier(0); }
;             u32x4 vf[2][4];
; #pragma unroll
;             for (int dt = 0; dt < 4; ++dt) VLD(vf[0][dt], 0, dt);
;             float mx = s0[0];
; #pragma unroll
;             for (int i = 1; i < 16; ++i) mx = fmaxf(mx, s0[i]);
; #pragma unroll
;             for (int i = 0; i < 16; ++i) mx = fmaxf(mx, s1[i]);
;             mx = fmaxf(mx, shfl_xor_l(mx, lane, 32));
;             const float mnew = fmaxf(mrow, mx), alpha = __builtin_amdgcn_exp2f(mrow - mnew); mrow = mnew;
;             float ls = 0.f;
; #pragma unroll
;             for (int i = 0; i < 16; ++i) { s0[i] = __builtin_amdgcn_exp2f(s0[i] - mnew); s1[i] = __builtin_amdgcn_exp2f(s1[i] - mnew); ls += s0[i] + s1[i]; }
.LBB0_1079:
	s_and_b32 s65, s64, 1
	global_load_dwordx4 v[146:149], v194, s[70:71]
	global_load_dwordx4 v[150:153], v194, s[72:73]
	global_load_dwordx4 v[154:157], v192, s[78:79]
	global_load_dwordx4 v[158:161], v190, s[74:75] offset:128
	global_load_dwordx4 v[162:165], v190, s[76:77] offset:128
	s_cmp_gt_u32 s64, s62
	s_cbranch_scc1 .LBB0_1083
	s_mul_i32 s66, s65, 0xa800
	s_add_i32 s66, s66, 0
	v_add3_u32 v171, s66, v199, v202
	ds_read_b128 v[66:69], v171
	ds_read_b128 v[166:169], v171 offset:32
	ds_read_b128 v[82:85], v171 offset:12800
	ds_read_b128 v[172:175], v171 offset:64
	ds_read_b128 v[176:179], v171 offset:12832
	ds_read_b128 v[204:207], v171 offset:12864
	s_waitcnt lgkmcnt(3)
	v_mfma_f32_32x32x16_bf16 v[82:97], v[82:85], v[142:145], v[216:231]
	v_mfma_f32_32x32x16_bf16 v[66:81], v[66:69], v[142:145], v[216:231]
	v_mfma_f32_32x32x16_bf16 v[66:81], v[166:169], v[138:141], v[66:81]
	ds_read_b128 v[166:169], v171 offset:96
	ds_read_b128 v[208:211], v171 offset:12896
	s_waitcnt lgkmcnt(3)
	v_mfma_f32_32x32x16_bf16 v[82:97], v[176:179], v[138:141], v[82:97]
	v_mfma_f32_32x32x16_bf16 v[66:81], v[172:175], v[134:137], v[66:81]
	ds_read_b128 v[172:175], v171 offset:128
	ds_read_b128 v[176:179], v171 offset:12928
	s_waitcnt lgkmcnt(4)
	v_mfma_f32_32x32x16_bf16 v[82:97], v[204:207], v[134:137], v[82:97]
	s_waitcnt lgkmcnt(3)
	v_mfma_f32_32x32x16_bf16 v[66:81], v[166:169], v[130:133], v[66:81]
	ds_read_b128 v[166:169], v171 offset:160
	ds_read_b128 v[204:207], v171 offset:12960
	s_waitcnt lgkmcnt(4)
	v_mfma_f32_32x32x16_bf16 v[82:97], v[208:211], v[130:133], v[82:97]
	s_waitcnt lgkmcnt(3)
	v_mfma_f32_32x32x16_bf16 v[66:81], v[172:175], v[126:129], v[66:81]
	ds_read_b128 v[172:175], v171 offset:192
	ds_read_b128 v[208:211], v171 offset:12992
	s_waitcnt lgkmcnt(4)
	v_mfma_f32_32x32x16_bf16 v[82:97], v[176:179], v[126:129], v[82:97]
	s_waitcnt lgkmcnt(3)
	v_mfma_f32_32x32x16_bf16 v[66:81], v[166:169], v[122:125], v[66:81]
	ds_read_b128 v[166:169], v171 offset:224
	ds_read_b128 v[176:179], v171 offset:13024
	s_waitcnt lgkmcnt(4)
	v_mfma_f32_32x32x16_bf16 v[82:97], v[204:207], v[122:125], v[82:97]
	s_waitcnt lgkmcnt(3)
	v_mfma_f32_32x32x16_bf16 v[66:81], v[172:175], v[118:121], v[66:81]
	ds_read_b128 v[172:175], v171 offset:256
	ds_read_b128 v[204:207], v171 offset:13056
	s_waitcnt lgkmcnt(4)
	v_mfma_f32_32x32x16_bf16 v[82:97], v[208:211], v[118:121], v[82:97]
	s_waitcnt lgkmcnt(3)
	v_mfma_f32_32x32x16_bf16 v[66:81], v[166:169], v[114:117], v[66:81]
	ds_read_b128 v[166:169], v171 offset:288
	ds_read_b128 v[208:211], v171 offset:13088
	s_waitcnt lgkmcnt(4)
	v_mfma_f32_32x32x16_bf16 v[82:97], v[176:179], v[114:117], v[82:97]
	s_waitcnt lgkmcnt(3)
	v_mfma_f32_32x32x16_bf16 v[66:81], v[172:175], v[110:113], v[66:81]
	ds_read_b128 v[172:175], v171 offset:320
	ds_read_b128 v[176:179], v171 offset:13120
	s_waitcnt lgkmcnt(4)
	v_mfma_f32_32x32x16_bf16 v[82:97], v[204:207], v[110:113], v[82:97]
	s_waitcnt lgkmcnt(3)
	v_mfma_f32_32x32x16_bf16 v[66:81], v[166:169], v[106:109], v[66:81]
	ds_read_b128 v[166:169], v171 offset:352
	ds_read_b128 v[212:215], v171 offset:13152
	s_waitcnt lgkmcnt(4)
	v_mfma_f32_32x32x16_bf16 v[82:97], v[208:211], v[106:109], v[82:97]
	s_waitcnt lgkmcnt(3)
	v_mfma_f32_32x32x16_bf16 v[66:81], v[172:175], v[102:105], v[66:81]
	s_waitcnt lgkmcnt(2)
	v_mfma_f32_32x32x16_bf16 v[82:97], v[176:179], v[102:105], v[82:97]
	s_waitcnt lgkmcnt(1)
	v_mfma_f32_32x32x16_bf16 v[66:81], v[166:169], v[98:101], v[66:81]
	v_add_u32_e32 v171, s66, v184
	v_add_u32_e32 v171, v171, v189
	v_add_u32_e32 v204, 0x6000, v171
	v_add_u32_e32 v205, 0x7000, v171
	v_add_u32_e32 v206, 0x8000, v171
	v_add_u32_e32 v207, 0x9000, v171
	ds_read2_b64 v[166:169], v204 offset0:128 offset1:130
	s_nop 4
	v_max_f32_e32 v172, v66, v67
	s_waitcnt lgkmcnt(1)
	v_mfma_f32_32x32x16_bf16 v[82:97], v[212:215], v[98:101], v[82:97]
	v_max3_f32 v172, v172, v68, v69
	v_max3_f32 v172, v172, v70, v71
	v_max3_f32 v172, v172, v72, v73
	v_max3_f32 v172, v172, v74, v75
	v_max3_f32 v172, v172, v76, v77
	v_max3_f32 v172, v172, v78, v79
	v_max3_f32 v172, v172, v80, v81
	s_nop 4
	v_max3_f32 v172, v172, v82, v83
	v_max3_f32 v172, v172, v84, v85
	v_max3_f32 v172, v172, v86, v87
	v_max3_f32 v172, v172, v88, v89
	v_max3_f32 v172, v172, v90, v91
	v_max3_f32 v172, v172, v92, v93
	v_max3_f32 v172, v172, v94, v95
	v_max3_f32 v172, v172, v96, v97
	ds_read2_b64 v[178:181], v205 offset0:160 offset1:162
	ds_read2_b64 v[174:177], v206 offset0:192 offset1:194
	v_cmp_lt_f32_e32 vcc, 0x41000000, v172
	s_cmp_eq_u32 s64, 0
	s_cbranch_scc1 .Lfold_0_upd
	s_cbranch_vccnz .Lfold_0_upd
.LBB0_1082:
	ds_read2_b64 v[170:173], v207 offset0:224 offset1:226
	v_exp_f32_e32 v66, v66
	v_exp_f32_e32 v82, v82
	v_exp_f32_e32 v67, v67
	v_exp_f32_e32 v83, v83
	v_exp_f32_e32 v68, v68
	v_exp_f32_e32 v84, v84
	v_exp_f32_e32 v69, v69
	v_exp_f32_e32 v85, v85
	v_add_f32_e32 v208, v82, v66
	v_exp_f32_e32 v70, v70
	v_exp_f32_e32 v86, v86

; DI unsigned pk2(float a, float b) { f32x2 f = {a, b}; bf16v2 r = __builtin_convertvector(f, bf16v2); return __builtin_bit_cast(unsigned, r); }
; #define VLD(dst, j, dt) do { LAS unsigned char* va_ = vb + (32 * (dt) + n) * VROW + (16 * (j) + 4 * g) * 2; const u32x2 lo_ = *(const LAS u32x2*)(va_), hi_ = *(const LAS u32x2*)(va_ + 16); dst = (u32x4){lo_.x, lo_.y, hi_.x, hi_.y}; } while (0)
; DI void attn_unit(LAS unsigned char* lds, int wid, int b, int h, int qb) {
;     ...
;             for (int i = 0; i < 16; ++i) { s0[i] = __builtin_amdgcn_exp2f(s0[i] - mnew); s1[i] = __builtin_amdgcn_exp2f(s1[i] - mnew); ls += s0[i] + s1[i]; }
;             lrow = lrow * alpha + ls;
;             if (__builtin_amdgcn_ballot_w64(alpha != 1.f) != 0ull) {
; #pragma unroll
;                 for (int dt = 0; dt < 4; ++dt)
; #pragma unroll
;                     for (int i = 0; i < 16; ++i) o[dt][i] *= alpha;
;             }
;             bf16x8 pf[4];
; #pragma unroll
;             for (int jj = 0; jj < 2; ++jj) { u32x4 w0, w1;
;                 w0.x = pk2(s0[8 * jj + 0], s0[8 * jj + 1]); w0.y = pk2(s0[8 * jj + 2], s0[8 * jj + 3]); w0.z = pk2(s0[8 * jj + 4], s0[8 * jj + 5]); w0.w = pk2(s0[8 * jj + 6], s0[8 * jj + 7]);
;                 w1.x = pk2(s1[8 * jj + 0], s1[8 * jj + 1]); w1.y = pk2(s1[8 * jj + 2], s1[8 * jj + 3]); w1.z = pk2(s1[8 * jj + 4], s1[8 * jj + 5]); w1.w = pk2(s1[8 * jj + 6], s1[8 * jj + 7]);
;                 pf[jj] = __builtin_bit_cast(bf16x8, w0); pf[2 + jj] = __builtin_bit_cast(bf16x8, w1); }
; #pragma unroll
;             for (int j = 0; j < 4; ++j) {
;                 if (j < 3) {
; #pragma unroll
;                     for (int dt = 0; dt < 4; ++dt) VLD(vf[(j + 1) & 1][dt], j + 1, dt);
;                 }
; #pragma unroll
;                 for (int dt = 0; dt < 4; ++dt) o[dt] = __builtin_amdgcn_mfma_f32_32x32x16_bf16(__builtin_bit_cast(bf16x8, vf[j & 1][dt]), pf[j], o[dt], 0, 0, 0);
;                 __builtin_amdgcn_sched_barrier(0); }
	v_add_f32_e32 v209, v83, v67
	v_exp_f32_e32 v71, v71
	v_exp_f32_e32 v87, v87
	v_add_f32_e32 v208, v209, v208
	v_add_f32_e32 v209, v84, v68
	v_exp_f32_e32 v72, v72
	v_exp_f32_e32 v88, v88
	v_add_f32_e32 v208, v209, v208
	v_add_f32_e32 v209, v85, v69
	v_exp_f32_e32 v73, v73
	v_exp_f32_e32 v89, v89
	v_add_f32_e32 v208, v209, v208
	v_add_f32_e32 v209, v86, v70
	v_exp_f32_e32 v74, v74
	v_exp_f32_e32 v90, v90
	v_add_f32_e32 v208, v209, v208
	v_add_f32_e32 v209, v87, v71
	v_exp_f32_e32 v75, v75
	v_exp_f32_e32 v91, v91
	v_add_f32_e32 v208, v209, v208
	v_add_f32_e32 v209, v88, v72
	v_exp_f32_e32 v76, v76
	v_exp_f32_e32 v92, v92
	v_add_f32_e32 v208, v209, v208
	v_add_f32_e32 v209, v89, v73
	v_exp_f32_e32 v77, v77
	v_exp_f32_e32 v93, v93
	v_add_f32_e32 v208, v209, v208
	v_add_f32_e32 v209, v90, v74
	v_exp_f32_e32 v78, v78
	v_exp_f32_e32 v94, v94
	v_add_f32_e32 v208, v209, v208
	v_add_f32_e32 v209, v91, v75
	v_exp_f32_e32 v79, v79
	v_exp_f32_e32 v95, v95
	v_add_f32_e32 v208, v209, v208
	v_add_f32_e32 v209, v92, v76
	v_exp_f32_e32 v80, v80
	v_exp_f32_e32 v96, v96
	v_add_f32_e32 v208, v209, v208
	v_add_f32_e32 v209, v93, v77
	v_exp_f32_e32 v81, v81
	v_exp_f32_e32 v97, v97
	v_add_f32_e32 v208, v209, v208
	v_add_f32_e32 v209, v94, v78
	v_add_f32_e32 v208, v209, v208
	v_add_f32_e32 v209, v95, v79
	v_add_f32_e32 v208, v209, v208
	v_cvt_pk_bf16_f32 v66, v66, v67
	v_cvt_pk_bf16_f32 v67, v68, v69
	v_cvt_pk_bf16_f32 v68, v70, v71
	v_cvt_pk_bf16_f32 v69, v72, v73
	v_add_f32_e32 v70, v96, v80
	v_add_f32_e32 v70, v70, v208
	s_waitcnt lgkmcnt(3)
	v_mfma_f32_32x32x16_bf16 v[50:65], v[166:169], v[66:69], v[50:65]
	v_add_f32_e32 v71, v97, v81
	v_add_f32_e32 v166, v71, v70
	v_cvt_pk_bf16_f32 v70, v82, v83
	v_cvt_pk_bf16_f32 v71, v84, v85
	v_cvt_pk_bf16_f32 v72, v86, v87
	v_cvt_pk_bf16_f32 v73, v88, v89
	v_cvt_pk_bf16_f32 v74, v74, v75
	s_waitcnt lgkmcnt(2)
	v_mfma_f32_32x32x16_bf16 v[34:49], v[178:181], v[66:69], v[34:49]
	v_cvt_pk_bf16_f32 v75, v76, v77
	v_cvt_pk_bf16_f32 v76, v78, v79
	v_cvt_pk_bf16_f32 v77, v80, v81
	v_cvt_pk_bf16_f32 v78, v90, v91
	v_cvt_pk_bf16_f32 v79, v92, v93
	v_cvt_pk_bf16_f32 v80, v94, v95
	v_cvt_pk_bf16_f32 v81, v96, v97
	s_waitcnt lgkmcnt(1)
	v_mfma_f32_32x32x16_bf16 v[18:33], v[174:177], v[66:69], v[18:33]
	ds_read2_b64 v[82:85], v204 offset0:132 offset1:134
	ds_read2_b64 v[86:89], v205 offset0:164 offset1:166
	ds_read2_b64 v[90:93], v206 offset0:196 offset1:198
	ds_read2_b64 v[94:97], v207 offset0:228 offset1:230
	v_add_f32_e32 v187, v187, v166
	s_waitcnt lgkmcnt(4)
	v_mfma_f32_32x32x16_bf16 v[2:17], v[170:173], v[66:69], v[2:17]
	s_waitcnt lgkmcnt(3)
	v_mfma_f32_32x32x16_bf16 v[50:65], v[82:85], v[74:77], v[50:65]
	s_waitcnt lgkmcnt(2)
	v_mfma_f32_32x32x16_bf16 v[34:49], v[86:89], v[74:77], v[34:49]
	s_waitcnt lgkmcnt(1)
	v_mfma_f32_32x32x16_bf16 v[18:33], v[90:93], v[74:77], v[18:33]
	ds_read2_b64 v[66:69], v204 offset0:136 offset1:138
	ds_read2_b64 v[82:85], v205 offset0:168 offset1:170
	ds_read2_b64 v[86:89], v206 offset0:200 offset1:202
	ds_read2_b64 v[90:93], v207 offset0:232 offset1:234
	s_waitcnt lgkmcnt(4)
	v_mfma_f32_32x32x16_bf16 v[2:17], v[94:97], v[74:77], v[2:17]
	s_waitcnt lgkmcnt(3)
	v_mfma_f32_32x32x16_bf16 v[50:65], v[66:69], v[70:73], v[50:65]
	s_waitcnt lgkmcnt(2)
	v_mfma_f32_32x32x16_bf16 v[34:49], v[82:85], v[70:73], v[34:49]
	s_waitcnt lgkmcnt(1)
	v_mfma_f32_32x32x16_bf16 v[18:33], v[86:89], v[70:73], v[18:33]
	ds_read2_b64 v[66:69], v204 offset0:140 offset1:142
	ds_read2_b64 v[74:77], v205 offset0:172 offset1:174
	ds_read2_b64 v[82:85], v206 offset0:204 offset1:206
	ds_read2_b64 v[86:89], v207 offset0:236 offset1:238
	s_waitcnt lgkmcnt(4)
	v_mfma_f32_32x32x16_bf16 v[2:17], v[90:93], v[70:73], v[2:17]
	s_waitcnt lgkmcnt(3)
	v_mfma_f32_32x32x16_bf16 v[50:65], v[66:69], v[78:81], v[50:65]
	s_waitcnt lgkmcnt(2)
	v_mfma_f32_32x32x16_bf16 v[34:49], v[74:77], v[78:81], v[34:49]
	s_waitcnt lgkmcnt(1)
	v_mfma_f32_32x32x16_bf16 v[18:33], v[82:85], v[78:81], v[18:33]
	s_waitcnt lgkmcnt(0)
	v_mfma_f32_32x32x16_bf16 v[2:17], v[86:89], v[78:81], v[2:17]

; DI float shfl_xor_l(float v, int lane, int m) { return __int_as_float(__builtin_amdgcn_ds_bpermute((lane ^ m) << 2, __float_as_int(v))); }
; DI void attn_unit(LAS unsigned char* lds, int wid, int b, int h, int qb) {
;     ...
;             mx = fmaxf(mx, shfl_xor_l(mx, lane, 32));
;             const float mnew = fmaxf(mrow, mx), alpha = __builtin_amdgcn_exp2f(mrow - mnew); mrow = mnew;
;             float ls = 0.f;
; #pragma unroll
;             for (int i = 0; i < 16; ++i) { s0[i] = __builtin_amdgcn_exp2f(s0[i] - mnew); s1[i] = __builtin_amdgcn_exp2f(s1[i] - mnew); ls += s0[i] + s1[i]; }
;             lrow = lrow * alpha + ls;
;             if (__builtin_amdgcn_ballot_w64(alpha != 1.f) != 0ull) {
; #pragma unroll
;                 for (int dt = 0; dt < 4; ++dt)
; #pragma unroll
;                     for (int i = 0; i < 16; ++i) o[dt][i] *= alpha;
;             }
.Lfold_0_upd:
	ds_bpermute_b32 v173, v185, v172
	s_waitcnt lgkmcnt(0)
	v_max_f32_e32 v237, v172, v173
	s_cmp_eq_u32 s64, 0
	s_cbranch_scc1 .Lfold_0_first
	v_max_f32_e32 v237, 0, v237
	v_exp_f32_e64 v196, -v237
	s_branch .Lfold_0_go

; #define LAS __attribute__((address_space(3)))
; DI float shfl_xor_l(float v, int lane, int m) { return __int_as_float(__builtin_amdgcn_ds_bpermute((lane ^ m) << 2, __float_as_int(v))); }
; #define A_LOAD(kt) do { const size_t ko = (size_t)(kt) * 64; st0 = *(const u32x4*)(kn_src + ko * 2048); st1 = *(const u32x4*)(kn_src + (ko + 32) * 2048); \
;         st2 = *(const u32x4*)(kr_src + ko * 64); st3 = *(const u32x4*)(v_src + ko); st4 = *(const u32x4*)(v_src + ko + (size_t)64 * 8192); } while (0)
; #define VLD(dst, j, dt) do { LAS unsigned char* va_ = vb + (32 * (dt) + n) * VROW + (16 * (j) + 4 * g) * 2; const u32x2 lo_ = *(const LAS u32x2*)(va_), hi_ = *(const LAS u32x2*)(va_ + 16); dst = (u32x4){lo_.x, lo_.y, hi_.x, hi_.y}; } while (0)
; DI void attn_unit(LAS unsigned char* lds, int wid, int b, int h, int qb) {
;     ...
;         if (kt + 1 < nkt) A_LOAD(kt + 1);
;         if (kt <= cq) {
;             LAS unsigned char* kb = lds + buf * ABUF; LAS unsigned char* vb = kb + KBYTES;
;             f32x16 s0, s1;
; #pragma unroll
;             for (int i = 0; i < 16; ++i) { s0[i] = 0.f; s1[i] = 0.f; }
;     ...
;             bf16x8 ka[3][2];
;             ka[0][0] = KLD(0, 0); ka[0][1] = KLD(0, 1); ka[1][0] = KLD(1, 0); ka[1][1] = KLD(1, 1);
; #pragma unroll
;             for (int ks = 0; ks < 12; ++ks) {
;                 if (ks + 2 < 12) { ka[(ks + 2) % 3][0] = KLD(ks + 2, 0); ka[(ks + 2) % 3][1] = KLD(ks + 2, 1); }
;                 s0 = __builtin_amdgcn_mfma_f32_32x32x16_bf16(ka[ks % 3][0], qf[ks], s0, 0, 0, 0); s1 = __builtin_amdgcn_mfma_f32_32x32x16_bf16(ka[ks % 3][1], qf[ks], s1, 0, 0, 0);
;                 __builtin_amdgcn_sched_barrier(0); }
;             u32x4 vf[2][4];
; #pragma unroll
;             for (int dt = 0; dt < 4; ++dt) VLD(vf[0][dt], 0, dt);
;             float mx = s0[0];
; #pragma unroll
;             for (int i = 1; i < 16; ++i) mx = fmaxf(mx, s0[i]);
; #pragma unroll
;             for (int i = 0; i < 16; ++i) mx = fmaxf(mx, s1[i]);
;             mx = fmaxf(mx, shfl_xor_l(mx, lane, 32));
.LBB0_1091:
	s_and_b32 s18, s57, 1
	global_load_dwordx4 v[2:5], v198, s[70:71]
	global_load_dwordx4 v[6:9], v198, s[72:73]
	global_load_dwordx4 v[10:13], v196, s[78:79]
	global_load_dwordx4 v[160:163], v194, s[74:75] offset:128
	global_load_dwordx4 v[164:167], v194, s[76:77] offset:128
	s_cmp_gt_u32 s57, s25
	s_cbranch_scc1 .LBB0_1095
	s_mul_i32 s19, s18, 0xa800
	s_add_i32 s19, s19, 0
	v_add3_u32 v0, s19, v193, v204
	ds_read_b128 v[80:83], v0
	ds_read_b128 v[168:171], v0 offset:32
	ds_read_b128 v[96:99], v0 offset:12800
	ds_read_b128 v[174:177], v0 offset:64
	ds_read_b128 v[178:181], v0 offset:12832
	ds_read_b128 v[206:209], v0 offset:12864
	s_waitcnt vmcnt(6) lgkmcnt(3)
	v_mfma_f32_32x32x16_bf16 v[96:111], v[96:99], v[156:159], v[216:231]
	v_mfma_f32_32x32x16_bf16 v[80:95], v[80:83], v[156:159], v[216:231]
	v_mfma_f32_32x32x16_bf16 v[80:95], v[168:171], v[152:155], v[80:95]
	ds_read_b128 v[168:171], v0 offset:96
	ds_read_b128 v[210:213], v0 offset:12896
	s_waitcnt lgkmcnt(3)
	v_mfma_f32_32x32x16_bf16 v[96:111], v[178:181], v[152:155], v[96:111]
	v_mfma_f32_32x32x16_bf16 v[80:95], v[174:177], v[148:151], v[80:95]
	ds_read_b128 v[174:177], v0 offset:128
	ds_read_b128 v[178:181], v0 offset:12928
	s_waitcnt lgkmcnt(4)
	v_mfma_f32_32x32x16_bf16 v[96:111], v[206:209], v[148:151], v[96:111]
	s_waitcnt lgkmcnt(3)
	v_mfma_f32_32x32x16_bf16 v[80:95], v[168:171], v[144:147], v[80:95]
	ds_read_b128 v[168:171], v0 offset:160
	ds_read_b128 v[206:209], v0 offset:12960
	s_waitcnt lgkmcnt(4)
	v_mfma_f32_32x32x16_bf16 v[96:111], v[210:213], v[144:147], v[96:111]
	s_waitcnt lgkmcnt(3)
	v_mfma_f32_32x32x16_bf16 v[80:95], v[174:177], v[140:143], v[80:95]
	ds_read_b128 v[174:177], v0 offset:192
	ds_read_b128 v[210:213], v0 offset:12992
	s_waitcnt lgkmcnt(4)
	v_mfma_f32_32x32x16_bf16 v[96:111], v[178:181], v[140:143], v[96:111]
	s_waitcnt lgkmcnt(3)
	v_mfma_f32_32x32x16_bf16 v[80:95], v[168:171], v[136:139], v[80:95]
	ds_read_b128 v[168:171], v0 offset:224
	ds_read_b128 v[178:181], v0 offset:13024
	s_waitcnt lgkmcnt(4)
	v_mfma_f32_32x32x16_bf16 v[96:111], v[206:209], v[136:139], v[96:111]
	s_waitcnt lgkmcnt(3)
	v_mfma_f32_32x32x16_bf16 v[80:95], v[174:177], v[132:135], v[80:95]
	ds_read_b128 v[174:177], v0 offset:256
	ds_read_b128 v[206:209], v0 offset:13056
	s_waitcnt lgkmcnt(4)
	v_mfma_f32_32x32x16_bf16 v[96:111], v[210:213], v[132:135], v[96:111]
	s_waitcnt lgkmcnt(3)
	v_mfma_f32_32x32x16_bf16 v[80:95], v[168:171], v[128:131], v[80:95]
	ds_read_b128 v[168:171], v0 offset:288
	ds_read_b128 v[210:213], v0 offset:13088
	s_waitcnt lgkmcnt(4)
	v_mfma_f32_32x32x16_bf16 v[96:111], v[178:181], v[128:131], v[96:111]
	s_waitcnt lgkmcnt(3)
	v_mfma_f32_32x32x16_bf16 v[80:95], v[174:177], v[124:127], v[80:95]
	ds_read_b128 v[174:177], v0 offset:320
	ds_read_b128 v[178:181], v0 offset:13120
	s_waitcnt lgkmcnt(4)
	v_mfma_f32_32x32x16_bf16 v[96:111], v[206:209], v[124:127], v[96:111]
	s_waitcnt lgkmcnt(3)
	v_mfma_f32_32x32x16_bf16 v[80:95], v[168:171], v[120:123], v[80:95]
	ds_read_b128 v[168:171], v0 offset:352
	ds_read_b128 v[206:209], v0 offset:13152
	s_waitcnt lgkmcnt(4)
	v_mfma_f32_32x32x16_bf16 v[96:111], v[210:213], v[120:123], v[96:111]
	s_waitcnt lgkmcnt(3)
	v_mfma_f32_32x32x16_bf16 v[80:95], v[174:177], v[116:119], v[80:95]
	s_waitcnt lgkmcnt(2)
	v_mfma_f32_32x32x16_bf16 v[96:111], v[178:181], v[116:119], v[96:111]
	s_waitcnt vmcnt(5) lgkmcnt(1)
	v_mfma_f32_32x32x16_bf16 v[80:95], v[168:171], v[112:115], v[80:95]
	v_add_u32_e32 v0, s19, v188
	v_add_u32_e32 v173, v0, v191
	v_add_u32_e32 v15, 0x6000, v173
	v_add_u32_e32 v205, 0x7000, v173
	ds_read2_b64 v[168:171], v15 offset0:128 offset1:130
	ds_read2_b64 v[180:183], v205 offset0:160 offset1:162
	s_nop 5
	v_max_f32_e32 v0, v80, v81
	s_waitcnt lgkmcnt(2)
	v_mfma_f32_32x32x16_bf16 v[96:111], v[206:209], v[112:115], v[96:111]
	v_max3_f32 v0, v0, v82, v83
	v_max3_f32 v0, v0, v84, v85
	v_max3_f32 v0, v0, v86, v87
	v_max3_f32 v0, v0, v88, v89
	v_max3_f32 v0, v0, v90, v91
	v_max3_f32 v0, v0, v92, v93
	v_max3_f32 v0, v0, v94, v95
	s_nop 4
	v_max3_f32 v0, v0, v96, v97
	v_max3_f32 v0, v0, v98, v99
	v_max3_f32 v0, v0, v100, v101
	v_max3_f32 v0, v0, v102, v103
	v_max3_f32 v0, v0, v104, v105
	v_max3_f32 v0, v0, v106, v107
	v_max3_f32 v0, v0, v108, v109
	v_max3_f32 v0, v0, v110, v111
	v_add_u32_e32 v206, 0x8000, v173
	v_add_u32_e32 v207, 0x9000, v173
	ds_read2_b64 v[176:179], v206 offset0:192 offset1:194
	v_cmp_lt_f32_e32 vcc, 0x41000000, v0
	ds_read2_b64 v[172:175], v207 offset0:224 offset1:226
	s_cmp_eq_u32 s57, 0
	s_cbranch_scc1 .Lfold_2_upd
	s_cbranch_vccnz .Lfold_2_upd
.LBB0_1094:
	v_exp_f32_e32 v80, v80
	v_exp_f32_e32 v96, v96
	v_exp_f32_e32 v81, v81
	v_exp_f32_e32 v97, v97
	v_exp_f32_e32 v82, v82
	v_exp_f32_e32 v98, v98
	v_exp_f32_e32 v83, v83
	v_exp_f32_e32 v99, v99
	v_add_f32_e32 v208, v96, v80
	v_exp_f32_e32 v84, v84
	v_exp_f32_e32 v100, v100

; DI unsigned pk2(float a, float b) { f32x2 f = {a, b}; bf16v2 r = __builtin_convertvector(f, bf16v2); return __builtin_bit_cast(unsigned, r); }
; #define VLD(dst, j, dt) do { LAS unsigned char* va_ = vb + (32 * (dt) + n) * VROW + (16 * (j) + 4 * g) * 2; const u32x2 lo_ = *(const LAS u32x2*)(va_), hi_ = *(const LAS u32x2*)(va_ + 16); dst = (u32x4){lo_.x, lo_.y, hi_.x, hi_.y}; } while (0)
; DI void attn_unit(LAS unsigned char* lds, int wid, int b, int h, int qb) {
;     ...
;             const float mnew = fmaxf(mrow, mx), alpha = __builtin_amdgcn_exp2f(mrow - mnew); mrow = mnew;
;             float ls = 0.f;
; #pragma unroll
;             for (int i = 0; i < 16; ++i) { s0[i] = __builtin_amdgcn_exp2f(s0[i] - mnew); s1[i] = __builtin_amdgcn_exp2f(s1[i] - mnew); ls += s0[i] + s1[i]; }
;             lrow = lrow * alpha + ls;
;             if (__builtin_amdgcn_ballot_w64(alpha != 1.f) != 0ull) {
; #pragma unroll
;                 for (int dt = 0; dt < 4; ++dt)
; #pragma unroll
;                     for (int i = 0; i < 16; ++i) o[dt][i] *= alpha;
;             }
;             bf16x8 pf[4];
; #pragma unroll
;             for (int jj = 0; jj < 2; ++jj) { u32x4 w0, w1;
;                 w0.x = pk2(s0[8 * jj + 0], s0[8 * jj + 1]); w0.y = pk2(s0[8 * jj + 2], s0[8 * jj + 3]); w0.z = pk2(s0[8 * jj + 4], s0[8 * jj + 5]); w0.w = pk2(s0[8 * jj + 6], s0[8 * jj + 7]);
;                 w1.x = pk2(s1[8 * jj + 0], s1[8 * jj + 1]); w1.y = pk2(s1[8 * jj + 2], s1[8 * jj + 3]); w1.z = pk2(s1[8 * jj + 4], s1[8 * jj + 5]); w1.w = pk2(s1[8 * jj + 6], s1[8 * jj + 7]);
;                 pf[jj] = __builtin_bit_cast(bf16x8, w0); pf[2 + jj] = __builtin_bit_cast(bf16x8, w1); }
; #pragma unroll
;             for (int j = 0; j < 4; ++j) {
;                 if (j < 3) {
; #pragma unroll
;                     for (int dt = 0; dt < 4; ++dt) VLD(vf[(j + 1) & 1][dt], j + 1, dt);
;                 }
; #pragma unroll
;                 for (int dt = 0; dt < 4; ++dt) o[dt] = __builtin_amdgcn_mfma_f32_32x32x16_bf16(__builtin_bit_cast(bf16x8, vf[j & 1][dt]), pf[j], o[dt], 0, 0, 0);
;                 __builtin_amdgcn_sched_barrier(0); }
	v_add_f32_e32 v209, v97, v81
	v_exp_f32_e32 v85, v85
	v_exp_f32_e32 v101, v101
	v_add_f32_e32 v208, v209, v208
	v_add_f32_e32 v209, v98, v82
	v_exp_f32_e32 v86, v86
	v_exp_f32_e32 v102, v102
	v_add_f32_e32 v208, v209, v208
	v_add_f32_e32 v209, v99, v83
	v_exp_f32_e32 v87, v87
	v_exp_f32_e32 v103, v103
	v_add_f32_e32 v208, v209, v208
	v_add_f32_e32 v209, v100, v84
	v_exp_f32_e32 v88, v88
	v_exp_f32_e32 v104, v104
	v_add_f32_e32 v208, v209, v208
	v_add_f32_e32 v209, v101, v85
	v_exp_f32_e32 v89, v89
	v_exp_f32_e32 v105, v105
	v_add_f32_e32 v208, v209, v208
	v_add_f32_e32 v209, v102, v86
	v_exp_f32_e32 v90, v90
	v_exp_f32_e32 v106, v106
	v_add_f32_e32 v208, v209, v208
	v_add_f32_e32 v209, v103, v87
	v_exp_f32_e32 v91, v91
	v_exp_f32_e32 v107, v107
	v_add_f32_e32 v208, v209, v208
	v_add_f32_e32 v209, v104, v88
	v_exp_f32_e32 v92, v92
	v_exp_f32_e32 v108, v108
	v_add_f32_e32 v208, v209, v208
	v_add_f32_e32 v209, v105, v89
	v_exp_f32_e32 v93, v93
	v_exp_f32_e32 v109, v109
	v_add_f32_e32 v208, v209, v208
	v_add_f32_e32 v209, v106, v90
	v_exp_f32_e32 v94, v94
	v_exp_f32_e32 v110, v110
	v_add_f32_e32 v208, v209, v208
	v_add_f32_e32 v209, v107, v91
	v_exp_f32_e32 v95, v95
	v_exp_f32_e32 v111, v111
	v_add_f32_e32 v208, v209, v208
	v_add_f32_e32 v209, v108, v92
	v_add_f32_e32 v208, v209, v208
	v_add_f32_e32 v209, v109, v93
	v_add_f32_e32 v208, v209, v208
	v_cvt_pk_bf16_f32 v80, v80, v81
	v_cvt_pk_bf16_f32 v81, v82, v83
	v_cvt_pk_bf16_f32 v82, v84, v85
	v_cvt_pk_bf16_f32 v83, v86, v87
	v_add_f32_e32 v84, v110, v94
	v_add_f32_e32 v84, v84, v208
	s_waitcnt lgkmcnt(3)
	v_mfma_f32_32x32x16_bf16 v[64:79], v[168:171], v[80:83], v[64:79]
	v_add_f32_e32 v85, v111, v95
	v_add_f32_e32 v168, v85, v84
	v_cvt_pk_bf16_f32 v84, v96, v97
	v_cvt_pk_bf16_f32 v85, v98, v99
	v_cvt_pk_bf16_f32 v86, v100, v101
	v_cvt_pk_bf16_f32 v87, v102, v103
	v_cvt_pk_bf16_f32 v88, v88, v89
	s_waitcnt lgkmcnt(2)
	v_mfma_f32_32x32x16_bf16 v[48:63], v[180:183], v[80:83], v[48:63]
	v_cvt_pk_bf16_f32 v89, v90, v91
	v_cvt_pk_bf16_f32 v90, v92, v93
	v_cvt_pk_bf16_f32 v91, v94, v95
	v_cvt_pk_bf16_f32 v92, v104, v105
	v_cvt_pk_bf16_f32 v93, v106, v107
	v_cvt_pk_bf16_f32 v94, v108, v109
	v_cvt_pk_bf16_f32 v95, v110, v111
	s_waitcnt lgkmcnt(1)
	v_mfma_f32_32x32x16_bf16 v[32:47], v[176:179], v[80:83], v[32:47]
	ds_read2_b64 v[96:99], v15 offset0:132 offset1:134
	ds_read2_b64 v[100:103], v205 offset0:164 offset1:166
	ds_read2_b64 v[104:107], v206 offset0:196 offset1:198
	ds_read2_b64 v[108:111], v207 offset0:228 offset1:230
	v_add_f32_e32 v185, v185, v168
	s_waitcnt lgkmcnt(4)
	v_mfma_f32_32x32x16_bf16 v[16:31], v[172:175], v[80:83], v[16:31]
	s_waitcnt lgkmcnt(3)
	v_mfma_f32_32x32x16_bf16 v[64:79], v[96:99], v[88:91], v[64:79]
	s_waitcnt lgkmcnt(2)
	v_mfma_f32_32x32x16_bf16 v[48:63], v[100:103], v[88:91], v[48:63]
	s_waitcnt lgkmcnt(1)
	v_mfma_f32_32x32x16_bf16 v[32:47], v[104:107], v[88:91], v[32:47]
	ds_read2_b64 v[80:83], v15 offset0:136 offset1:138
	ds_read2_b64 v[96:99], v205 offset0:168 offset1:170
	ds_read2_b64 v[100:103], v206 offset0:200 offset1:202
	ds_read2_b64 v[104:107], v207 offset0:232 offset1:234
	s_waitcnt lgkmcnt(4)
	v_mfma_f32_32x32x16_bf16 v[16:31], v[108:111], v[88:91], v[16:31]
	s_waitcnt lgkmcnt(3)
	v_mfma_f32_32x32x16_bf16 v[64:79], v[80:83], v[84:87], v[64:79]
	s_waitcnt lgkmcnt(2)
	v_mfma_f32_32x32x16_bf16 v[48:63], v[96:99], v[84:87], v[48:63]
	s_waitcnt lgkmcnt(1)
	v_mfma_f32_32x32x16_bf16 v[32:47], v[100:103], v[84:87], v[32:47]
	ds_read2_b64 v[80:83], v15 offset0:140 offset1:142
	ds_read2_b64 v[88:91], v205 offset0:172 offset1:174
	ds_read2_b64 v[96:99], v206 offset0:204 offset1:206
	ds_read2_b64 v[100:103], v207 offset0:236 offset1:238
	s_waitcnt lgkmcnt(4)
	v_mfma_f32_32x32x16_bf16 v[16:31], v[104:107], v[84:87], v[16:31]
	s_waitcnt lgkmcnt(3)
	v_mfma_f32_32x32x16_bf16 v[64:79], v[80:83], v[92:95], v[64:79]
	s_waitcnt lgkmcnt(2)
	v_mfma_f32_32x32x16_bf16 v[48:63], v[88:91], v[92:95], v[48:63]
	s_waitcnt lgkmcnt(1)
	v_mfma_f32_32x32x16_bf16 v[32:47], v[96:99], v[92:95], v[32:47]
	s_waitcnt lgkmcnt(0)
	v_mfma_f32_32x32x16_bf16 v[16:31], v[100:103], v[92:95], v[16:31]

; DI float shfl_xor_l(float v, int lane, int m) { return __int_as_float(__builtin_amdgcn_ds_bpermute((lane ^ m) << 2, __float_as_int(v))); }
; DI void attn_unit(LAS unsigned char* lds, int wid, int b, int h, int qb) {
;     ...
;             mx = fmaxf(mx, shfl_xor_l(mx, lane, 32));
;             const float mnew = fmaxf(mrow, mx), alpha = __builtin_amdgcn_exp2f(mrow - mnew); mrow = mnew;
;             float ls = 0.f;
; #pragma unroll
;             for (int i = 0; i < 16; ++i) { s0[i] = __builtin_amdgcn_exp2f(s0[i] - mnew); s1[i] = __builtin_amdgcn_exp2f(s1[i] - mnew); ls += s0[i] + s1[i]; }
;             lrow = lrow * alpha + ls;
;             if (__builtin_amdgcn_ballot_w64(alpha != 1.f) != 0ull) {
; #pragma unroll
;                 for (int dt = 0; dt < 4; ++dt)
; #pragma unroll
;                     for (int i = 0; i < 16; ++i) o[dt][i] *= alpha;
;             }
.Lfold_2_upd:
	ds_bpermute_b32 v14, v189, v0
	s_waitcnt lgkmcnt(0)
	v_max_f32_e32 v237, v0, v14
	s_cmp_eq_u32 s57, 0
	s_cbranch_scc1 .Lfold_2_first
	v_max_f32_e32 v237, 0, v237
	v_exp_f32_e64 v0, -v237
	s_branch .Lfold_2_go
